# F1 GEMM: the leading wave half runs its SwiGLU epilogue before its realign barrier, i.e. under the trailing half's last MMA segment, instead of both halves running epilogues together
# baseline (speedup 1.0000x reference)
.LBB0_786:
	v_exp_f32_e32 v144, v122
	v_exp_f32_e32 v145, v123
	v_pk_mul_f32 v[122:123], v[122:123], v[126:127]
	v_exp_f32_e32 v126, v114
	v_exp_f32_e32 v127, v115
	v_pk_mul_f32 v[120:121], v[116:117], v[120:121]
	v_exp_f32_e32 v116, v116
	v_exp_f32_e32 v117, v117
	v_pk_add_f32 v[126:127], v[126:127], 1.0 op_sel_hi:[1,0]
	v_rcp_f32_e32 v126, v126
	v_rcp_f32_e32 v127, v127
	v_pk_add_f32 v[116:117], v[116:117], 1.0 op_sel_hi:[1,0]
	v_pk_mul_f32 v[128:129], v[124:125], v[128:129]
	v_exp_f32_e32 v124, v124
	v_exp_f32_e32 v125, v125
	v_rcp_f32_e32 v116, v116
	v_rcp_f32_e32 v117, v117
	s_ashr_i32 s25, s24, 31
	v_pk_mul_f32 v[114:115], v[114:115], v[118:119]
	v_readlane_b32 s4, v254, 2
	s_lshl_b64 s[2:3], s[24:25], 8
	v_pk_mul_f32 v[114:115], v[126:127], v[114:115]
	v_readlane_b32 s5, v254, 3
	v_lshl_add_u64 v[142:143], v[134:135], 0, s[2:3]
	v_cvt_pk_bf16_f32 v118, v114, v115
	v_mov_b64_e32 v[114:115], s[4:5]
	s_movk_i32 s15, 0x1600
	v_pk_add_f32 v[144:145], v[144:145], 1.0 op_sel_hi:[1,0]
	v_pk_add_f32 v[124:125], v[124:125], 1.0 op_sel_hi:[1,0]
	v_pk_mul_f32 v[120:121], v[116:117], v[120:121]
	v_mad_u64_u32 v[114:115], s[4:5], v142, s15, v[114:115]
	v_rcp_f32_e32 v144, v144
	v_rcp_f32_e32 v145, v145
	v_rcp_f32_e32 v124, v124
	v_rcp_f32_e32 v125, v125
	v_cvt_pk_bf16_f32 v119, v120, v121
	v_mov_b32_e32 v120, v115
	s_lshl_b32 s2, s22, 7
	v_mad_u64_u32 v[120:121], s[4:5], v143, s15, v[120:121]
	s_ashr_i32 s3, s2, 31
	v_mov_b32_e32 v115, v120
	v_lshl_add_u64 v[114:115], s[2:3], 1, v[114:115]
	v_pk_mul_f32 v[122:123], v[144:145], v[122:123]
	v_pk_mul_f32 v[124:125], v[124:125], v[128:129]
	v_lshl_add_u64 v[114:115], v[114:115], 0, s[68:69]
	v_cvt_pk_bf16_f32 v116, v122, v123
	v_cvt_pk_bf16_f32 v117, v124, v125
	v_lshl_add_u64 v[114:115], v[114:115], 0, v[0:1]
	global_store_dwordx4 v[114:115], v[116:119], off
	v_pk_mul_f32 v[112:113], v[108:109], v[112:113]
	v_exp_f32_e32 v108, v108
	v_exp_f32_e32 v116, v106
	v_exp_f32_e32 v117, v107
	v_pk_mul_f32 v[106:107], v[106:107], v[110:111]
	v_exp_f32_e32 v110, v98
	v_exp_f32_e32 v111, v99
	v_pk_mul_f32 v[98:99], v[98:99], v[102:103]
	v_exp_f32_e32 v109, v109
	v_pk_add_f32 v[110:111], v[110:111], 1.0 op_sel_hi:[1,0]
	v_rcp_f32_e32 v110, v110
	v_rcp_f32_e32 v111, v111
	v_pk_add_f32 v[116:117], v[116:117], 1.0 op_sel_hi:[1,0]
	v_add_f32_e32 v108, 1.0, v108
	v_pk_mul_f32 v[102:103], v[110:111], v[98:99]
	v_exp_f32_e32 v98, v100
	v_exp_f32_e32 v99, v101
	v_add_f32_e32 v109, 1.0, v109
	v_rcp_f32_e32 v116, v116
	v_pk_add_f32 v[98:99], v[98:99], 1.0 op_sel_hi:[1,0]
	v_rcp_f32_e32 v117, v117
	v_rcp_f32_e32 v108, v108
	v_rcp_f32_e32 v109, v109
	v_rcp_f32_e32 v98, v98
	v_rcp_f32_e32 v99, v99
	v_pk_mul_f32 v[104:105], v[100:101], v[104:105]
	s_mov_b32 s2, 0x16000
	v_pk_mul_f32 v[106:107], v[116:117], v[106:107]
	v_pk_mul_f32 v[108:109], v[108:109], v[112:113]
	v_pk_mul_f32 v[104:105], v[98:99], v[104:105]
	v_cvt_pk_bf16_f32 v100, v102, v103
	v_add_co_u32_e32 v102, vcc, s2, v114
	v_cvt_pk_bf16_f32 v98, v106, v107
	v_cvt_pk_bf16_f32 v99, v108, v109
	v_cvt_pk_bf16_f32 v101, v104, v105
	v_addc_co_u32_e32 v103, vcc, 0, v115, vcc
	global_store_dwordx4 v[102:103], v[98:101], off
	v_pk_mul_f32 v[96:97], v[92:93], v[96:97]
	v_exp_f32_e32 v92, v92
	v_exp_f32_e32 v98, v90
	v_exp_f32_e32 v99, v91
	v_pk_mul_f32 v[90:91], v[90:91], v[94:95]
	v_exp_f32_e32 v94, v82
	v_exp_f32_e32 v95, v83
	v_pk_mul_f32 v[82:83], v[82:83], v[86:87]
	v_exp_f32_e32 v93, v93
	v_pk_add_f32 v[94:95], v[94:95], 1.0 op_sel_hi:[1,0]
	v_rcp_f32_e32 v94, v94
	v_rcp_f32_e32 v95, v95
	v_pk_add_f32 v[98:99], v[98:99], 1.0 op_sel_hi:[1,0]
	v_add_f32_e32 v92, 1.0, v92
	v_pk_mul_f32 v[86:87], v[94:95], v[82:83]
	v_exp_f32_e32 v82, v84
	v_exp_f32_e32 v83, v85
	v_add_f32_e32 v93, 1.0, v93
	v_rcp_f32_e32 v98, v98
	v_pk_add_f32 v[82:83], v[82:83], 1.0 op_sel_hi:[1,0]
	v_rcp_f32_e32 v99, v99
	v_rcp_f32_e32 v92, v92
	v_rcp_f32_e32 v93, v93
	v_rcp_f32_e32 v82, v82
	v_rcp_f32_e32 v83, v83
	v_pk_mul_f32 v[88:89], v[84:85], v[88:89]
	s_mov_b32 s2, 0x2c000
	v_pk_mul_f32 v[90:91], v[98:99], v[90:91]
	v_pk_mul_f32 v[92:93], v[92:93], v[96:97]
	v_pk_mul_f32 v[88:89], v[82:83], v[88:89]
	v_cvt_pk_bf16_f32 v84, v86, v87
	v_add_co_u32_e32 v86, vcc, s2, v114
	v_cvt_pk_bf16_f32 v82, v90, v91
	v_cvt_pk_bf16_f32 v83, v92, v93
	v_cvt_pk_bf16_f32 v85, v88, v89
	v_addc_co_u32_e32 v87, vcc, 0, v115, vcc
	global_store_dwordx4 v[86:87], v[82:85], off
	v_pk_mul_f32 v[80:81], v[76:77], v[80:81]
	v_exp_f32_e32 v76, v76
	v_exp_f32_e32 v82, v74
	v_exp_f32_e32 v83, v75
	v_pk_mul_f32 v[74:75], v[74:75], v[78:79]
	v_exp_f32_e32 v78, v66
	v_exp_f32_e32 v79, v67
	v_pk_mul_f32 v[66:67], v[66:67], v[70:71]
	v_exp_f32_e32 v77, v77
	v_pk_add_f32 v[78:79], v[78:79], 1.0 op_sel_hi:[1,0]
	v_rcp_f32_e32 v78, v78
	v_rcp_f32_e32 v79, v79
	v_pk_add_f32 v[82:83], v[82:83], 1.0 op_sel_hi:[1,0]
	v_add_f32_e32 v76, 1.0, v76
	v_pk_mul_f32 v[70:71], v[78:79], v[66:67]
	v_exp_f32_e32 v66, v68
	v_exp_f32_e32 v67, v69
	v_add_f32_e32 v77, 1.0, v77
	v_rcp_f32_e32 v82, v82
	v_pk_add_f32 v[66:67], v[66:67], 1.0 op_sel_hi:[1,0]
	v_rcp_f32_e32 v83, v83
	v_rcp_f32_e32 v76, v76
	v_rcp_f32_e32 v77, v77
	v_rcp_f32_e32 v66, v66
	v_rcp_f32_e32 v67, v67
	v_pk_mul_f32 v[72:73], v[68:69], v[72:73]
	s_mov_b32 s2, 0x42000
	v_pk_mul_f32 v[74:75], v[82:83], v[74:75]
	v_pk_mul_f32 v[76:77], v[76:77], v[80:81]
	v_pk_mul_f32 v[72:73], v[66:67], v[72:73]
	v_cvt_pk_bf16_f32 v68, v70, v71
	v_add_co_u32_e32 v70, vcc, s2, v114
	v_cvt_pk_bf16_f32 v66, v74, v75
	v_cvt_pk_bf16_f32 v67, v76, v77
	v_cvt_pk_bf16_f32 v69, v72, v73
	v_addc_co_u32_e32 v71, vcc, 0, v115, vcc
	global_store_dwordx4 v[70:71], v[66:69], off
	v_pk_mul_f32 v[64:65], v[60:61], v[64:65]
	v_exp_f32_e32 v60, v60
	v_exp_f32_e32 v66, v58
	v_exp_f32_e32 v67, v59
	v_pk_mul_f32 v[58:59], v[58:59], v[62:63]
	v_exp_f32_e32 v62, v50
	v_exp_f32_e32 v63, v51
	v_pk_mul_f32 v[50:51], v[50:51], v[54:55]
	v_exp_f32_e32 v61, v61
	v_pk_add_f32 v[62:63], v[62:63], 1.0 op_sel_hi:[1,0]
	v_rcp_f32_e32 v62, v62
	v_rcp_f32_e32 v63, v63
	v_pk_add_f32 v[66:67], v[66:67], 1.0 op_sel_hi:[1,0]
	v_add_f32_e32 v60, 1.0, v60
	v_pk_mul_f32 v[54:55], v[62:63], v[50:51]
	v_exp_f32_e32 v50, v52
	v_exp_f32_e32 v51, v53
	v_add_f32_e32 v61, 1.0, v61
	v_rcp_f32_e32 v66, v66
	v_pk_add_f32 v[50:51], v[50:51], 1.0 op_sel_hi:[1,0]
	v_rcp_f32_e32 v67, v67
	v_rcp_f32_e32 v60, v60
	v_rcp_f32_e32 v61, v61
	v_rcp_f32_e32 v50, v50
	v_rcp_f32_e32 v51, v51
	v_pk_mul_f32 v[56:57], v[52:53], v[56:57]
	s_mov_b32 s2, 0xb0000
	v_pk_mul_f32 v[58:59], v[66:67], v[58:59]
	v_pk_mul_f32 v[60:61], v[60:61], v[64:65]
	v_pk_mul_f32 v[56:57], v[50:51], v[56:57]
	v_cvt_pk_bf16_f32 v52, v54, v55
	v_add_co_u32_e32 v54, vcc, s2, v114
	v_cvt_pk_bf16_f32 v50, v58, v59
	v_cvt_pk_bf16_f32 v51, v60, v61
	v_cvt_pk_bf16_f32 v53, v56, v57
	v_addc_co_u32_e32 v55, vcc, 0, v115, vcc
	global_store_dwordx4 v[54:55], v[50:53], off
	v_pk_mul_f32 v[48:49], v[44:45], v[48:49]
	v_exp_f32_e32 v44, v44
	v_exp_f32_e32 v50, v42
	v_exp_f32_e32 v51, v43
	v_pk_mul_f32 v[42:43], v[42:43], v[46:47]
	v_exp_f32_e32 v46, v34
	v_exp_f32_e32 v47, v35
	v_pk_mul_f32 v[34:35], v[34:35], v[38:39]
	v_exp_f32_e32 v45, v45
	v_pk_add_f32 v[46:47], v[46:47], 1.0 op_sel_hi:[1,0]
	v_rcp_f32_e32 v46, v46
	v_rcp_f32_e32 v47, v47
	v_pk_add_f32 v[50:51], v[50:51], 1.0 op_sel_hi:[1,0]
	v_add_f32_e32 v44, 1.0, v44
	v_pk_mul_f32 v[38:39], v[46:47], v[34:35]
	v_exp_f32_e32 v34, v36
	v_exp_f32_e32 v35, v37
	v_add_f32_e32 v45, 1.0, v45
	v_rcp_f32_e32 v50, v50
	v_pk_add_f32 v[34:35], v[34:35], 1.0 op_sel_hi:[1,0]
	v_rcp_f32_e32 v51, v51
	v_rcp_f32_e32 v44, v44
	v_rcp_f32_e32 v45, v45
	v_rcp_f32_e32 v34, v34
	v_rcp_f32_e32 v35, v35
	v_pk_mul_f32 v[40:41], v[36:37], v[40:41]
	s_mov_b32 s2, 0xc6000
	v_pk_mul_f32 v[42:43], v[50:51], v[42:43]
	v_pk_mul_f32 v[44:45], v[44:45], v[48:49]
	v_pk_mul_f32 v[40:41], v[34:35], v[40:41]
	v_cvt_pk_bf16_f32 v36, v38, v39
	v_add_co_u32_e32 v38, vcc, s2, v114
	v_cvt_pk_bf16_f32 v34, v42, v43
	v_cvt_pk_bf16_f32 v35, v44, v45
	v_cvt_pk_bf16_f32 v37, v40, v41
	v_addc_co_u32_e32 v39, vcc, 0, v115, vcc
	global_store_dwordx4 v[38:39], v[34:37], off
	v_pk_mul_f32 v[32:33], v[28:29], v[32:33]
	v_exp_f32_e32 v28, v28
	v_exp_f32_e32 v34, v26
	v_exp_f32_e32 v35, v27
	v_pk_mul_f32 v[26:27], v[26:27], v[30:31]
	v_exp_f32_e32 v30, v18
	v_exp_f32_e32 v31, v19
	v_pk_mul_f32 v[18:19], v[18:19], v[22:23]
	v_exp_f32_e32 v29, v29
	v_pk_add_f32 v[30:31], v[30:31], 1.0 op_sel_hi:[1,0]
	v_rcp_f32_e32 v30, v30
	v_rcp_f32_e32 v31, v31
	v_pk_add_f32 v[34:35], v[34:35], 1.0 op_sel_hi:[1,0]
	v_add_f32_e32 v28, 1.0, v28
	v_pk_mul_f32 v[22:23], v[30:31], v[18:19]
	v_exp_f32_e32 v18, v20
	v_exp_f32_e32 v19, v21
	v_add_f32_e32 v29, 1.0, v29
	v_rcp_f32_e32 v34, v34
	v_pk_add_f32 v[18:19], v[18:19], 1.0 op_sel_hi:[1,0]
	v_rcp_f32_e32 v35, v35
	v_rcp_f32_e32 v28, v28
	v_rcp_f32_e32 v29, v29
	v_rcp_f32_e32 v18, v18
	v_rcp_f32_e32 v19, v19
	v_pk_mul_f32 v[24:25], v[20:21], v[24:25]
	s_mov_b32 s2, 0xdc000
	v_pk_mul_f32 v[26:27], v[34:35], v[26:27]
	v_pk_mul_f32 v[28:29], v[28:29], v[32:33]
	v_pk_mul_f32 v[24:25], v[18:19], v[24:25]
	v_cvt_pk_bf16_f32 v20, v22, v23
	v_add_co_u32_e32 v22, vcc, s2, v114
	v_cvt_pk_bf16_f32 v18, v26, v27
	v_cvt_pk_bf16_f32 v19, v28, v29
	v_cvt_pk_bf16_f32 v21, v24, v25
	v_addc_co_u32_e32 v23, vcc, 0, v115, vcc
	global_store_dwordx4 v[22:23], v[18:21], off
	v_pk_mul_f32 v[16:17], v[12:13], v[16:17]
	v_exp_f32_e32 v12, v12
	v_exp_f32_e32 v18, v10
	v_exp_f32_e32 v19, v11
	v_pk_mul_f32 v[10:11], v[10:11], v[14:15]
	v_exp_f32_e32 v14, v2
	v_exp_f32_e32 v15, v3
	v_pk_mul_f32 v[2:3], v[2:3], v[6:7]
	v_exp_f32_e32 v13, v13
	v_pk_add_f32 v[14:15], v[14:15], 1.0 op_sel_hi:[1,0]
	v_rcp_f32_e32 v14, v14
	v_rcp_f32_e32 v15, v15
	v_pk_add_f32 v[18:19], v[18:19], 1.0 op_sel_hi:[1,0]
	v_add_f32_e32 v12, 1.0, v12
	v_pk_mul_f32 v[6:7], v[14:15], v[2:3]
	v_exp_f32_e32 v2, v4
	v_exp_f32_e32 v3, v5
	v_add_f32_e32 v13, 1.0, v13
	v_rcp_f32_e32 v18, v18
	v_pk_add_f32 v[2:3], v[2:3], 1.0 op_sel_hi:[1,0]
	v_rcp_f32_e32 v19, v19
	v_rcp_f32_e32 v12, v12
	v_rcp_f32_e32 v13, v13
	v_rcp_f32_e32 v2, v2
	v_rcp_f32_e32 v3, v3
	v_pk_mul_f32 v[8:9], v[4:5], v[8:9]
	v_cvt_pk_bf16_f32 v4, v6, v7
	v_add_co_u32_e32 v6, vcc, 0xf2000, v114
	v_pk_mul_f32 v[10:11], v[18:19], v[10:11]
	v_pk_mul_f32 v[12:13], v[12:13], v[16:17]
	v_pk_mul_f32 v[8:9], v[2:3], v[8:9]
	v_addc_co_u32_e32 v7, vcc, 0, v115, vcc
	v_cvt_pk_bf16_f32 v2, v10, v11
	v_cvt_pk_bf16_f32 v3, v12, v13
	v_cvt_pk_bf16_f32 v5, v8, v9
	s_and_b64 vcc, exec, s[12:13]
	s_cbranch_vccz .Lf1_nb
	s_barrier
.Lf1_nb:
	s_mov_b64 s[2:3], -1
	s_andn2_b64 vcc, exec, s[0:1]
	global_store_dwordx4 v[6:7], v[2:5], off
	s_cbranch_vccnz .LBB0_779
	s_andn2_b64 vcc, exec, s[10:11]
	s_cbranch_vccnz .LBB0_778
	s_barrier
	s_branch .LBB0_778
